# v22 + P5 epilogue: conv bias folded into the multiply-accumulate chain (fma with the bias as addend; 64 scalar + 17 packed groups, one VALU op less per conv output)
# speedup vs baseline: 1.0042x; 1.0042x over previous
.LBB0_168:
	s_or_b64 exec, exec, s[0:1]
	v_add_u32_e32 v66, 0, v66
	v_add_u32_e32 v122, v66, v80
	ds_read_b128 v[66:69], v122
	ds_read_b128 v[70:73], v122 offset:256
	v_fma_f32 v114, v22, v128, v30
	v_fmac_f32_e32 v114, v18, v111
	v_lshlrev_b32_e32 v100, 3, v86
	s_waitcnt lgkmcnt(1)
	v_lshlrev_b32_e32 v115, 16, v66
	v_fma_f32 v111, v26, v115, v114
	v_fma_f32 v114, v23, v127, v31
	v_and_b32_e32 v107, 0xffff0000, v66
	v_fmac_f32_e32 v114, v19, v74
	v_fma_f32 v74, v27, v107, v114
	v_fma_f32 v114, v34, v130, v42
	s_waitcnt lgkmcnt(0)
	v_lshlrev_b32_e32 v106, 16, v70
	v_fmac_f32_e32 v114, v62, v113
	v_fma_f32 v113, v38, v106, v114
	v_fma_f32 v114, v35, v129, v43
	v_and_b32_e32 v99, 0xffff0000, v70
	v_fmac_f32_e32 v114, v63, v112
	v_fma_f32 v112, v39, v99, v114
	v_mul_f32_e32 v114, 0xbfb8aa3b, v111
	v_exp_f32_e32 v114, v114
	v_lshlrev_b32_e32 v98, 16, v67
	v_and_b32_e32 v97, 0xffff0000, v67
	v_lshlrev_b32_e32 v96, 16, v71
	v_add_f32_e32 v114, 1.0, v114
	v_rcp_f32_e32 v114, v114
	v_and_b32_e32 v95, 0xffff0000, v71
	v_lshlrev_b32_e32 v94, 16, v68
	v_and_b32_e32 v93, 0xffff0000, v68
	v_mul_f32_e32 v111, v111, v114
	v_mul_f32_e32 v111, v113, v111
	v_mul_f32_e32 v113, 0xbfb8aa3b, v74
	v_exp_f32_e32 v113, v113
	v_lshlrev_b32_e32 v92, 16, v72
	v_and_b32_e32 v91, 0xffff0000, v72
	v_lshlrev_b32_e32 v90, 16, v69
	v_add_f32_e32 v113, 1.0, v113
	v_rcp_f32_e32 v113, v113
	v_and_b32_e32 v89, 0xffff0000, v69
	v_lshlrev_b32_e32 v88, 16, v73
	v_and_b32_e32 v87, 0xffff0000, v73
	v_mul_f32_e32 v74, v74, v113
	v_mul_f32_e32 v74, v112, v74
	v_cvt_pk_bf16_f32 v74, v111, v74
	v_fma_f32 v111, v24, v124, v32
	v_fmac_f32_e32 v111, v20, v108
	v_fma_f32 v108, v28, v98, v111
	v_fma_f32 v111, v25, v123, v33
	v_fmac_f32_e32 v111, v21, v75
	v_fma_f32 v75, v29, v97, v111
	v_fma_f32 v111, v36, v126, v44
	v_fmac_f32_e32 v111, v64, v110
	v_fma_f32 v110, v40, v96, v111
	v_fma_f32 v111, v37, v125, v45
	v_fmac_f32_e32 v111, v65, v109
	v_fma_f32 v109, v41, v95, v111
	v_mul_f32_e32 v111, 0xbfb8aa3b, v108
	v_exp_f32_e32 v111, v111
	s_lshl_b32 s37, s36, 8
	v_add_f32_e32 v111, 1.0, v111
	v_rcp_f32_e32 v111, v111
	s_nop 0
	v_mul_f32_e32 v108, v108, v111
	v_mul_f32_e32 v108, v110, v108
	v_mul_f32_e32 v110, 0xbfb8aa3b, v75
	v_exp_f32_e32 v110, v110
	s_nop 0
	v_add_f32_e32 v110, 1.0, v110
	v_rcp_f32_e32 v110, v110
	s_nop 0
	v_mul_f32_e32 v75, v75, v110
	v_mul_f32_e32 v75, v109, v75
	v_cvt_pk_bf16_f32 v75, v108, v75
	v_fma_f32 v108, v6, v85, v14
	v_fmac_f32_e32 v108, v2, v103
	v_fma_f32 v103, v10, v94, v108
	v_fma_f32 v108, v7, v84, v15
	v_fmac_f32_e32 v108, v3, v76
	v_fma_f32 v76, v11, v93, v108
	v_fma_f32 v108, v46, v121, v54
	v_fmac_f32_e32 v108, v58, v105
	v_fma_f32 v105, v50, v92, v108
	v_fma_f32 v108, v47, v120, v55
	v_fmac_f32_e32 v108, v59, v104
	v_fma_f32 v104, v51, v91, v108
	v_mul_f32_e32 v108, 0xbfb8aa3b, v103
	v_exp_f32_e32 v108, v108
	s_nop 0
	v_add_f32_e32 v108, 1.0, v108
	v_rcp_f32_e32 v108, v108
	s_nop 0
	v_mul_f32_e32 v103, v103, v108
	v_mul_f32_e32 v103, v105, v103
	v_mul_f32_e32 v105, 0xbfb8aa3b, v76
	v_exp_f32_e32 v105, v105
	s_nop 0
	v_add_f32_e32 v105, 1.0, v105
	v_rcp_f32_e32 v105, v105
	s_nop 0
	v_mul_f32_e32 v76, v76, v105
	v_mul_f32_e32 v76, v104, v76
	v_cvt_pk_bf16_f32 v76, v103, v76
	v_fma_f32 v103, v8, v81, v16
	v_fmac_f32_e32 v103, v4, v78
	v_fma_f32 v78, v12, v90, v103
	v_fma_f32 v103, v9, v79, v17
	v_fmac_f32_e32 v103, v5, v77
	v_fma_f32 v77, v13, v89, v103
	v_fma_f32 v103, v48, v83, v56
	v_fmac_f32_e32 v103, v60, v102
	v_fma_f32 v102, v52, v88, v103
	v_fma_f32 v103, v49, v82, v57
	v_fmac_f32_e32 v103, v61, v101
	v_fma_f32 v101, v53, v87, v103
	v_mul_f32_e32 v103, 0xbfb8aa3b, v78
	v_exp_f32_e32 v103, v103
	s_nop 0
	v_add_f32_e32 v103, 1.0, v103
	v_rcp_f32_e32 v103, v103
	s_nop 0
	v_mul_f32_e32 v78, v78, v103
	v_mul_f32_e32 v78, v102, v78
	v_mul_f32_e32 v102, 0xbfb8aa3b, v77
	v_exp_f32_e32 v102, v102
	s_nop 0
	v_add_f32_e32 v102, 1.0, v102
	v_rcp_f32_e32 v102, v102
	s_nop 0
	v_mul_f32_e32 v77, v77, v102
	v_mul_f32_e32 v77, v101, v77
	v_cvt_pk_bf16_f32 v77, v78, v77
	s_and_saveexec_b64 s[0:1], vcc
	s_cbranch_execz .LBB0_170
	v_add_u32_e32 v78, s37, v100
	v_mov_b64_e32 v[102:103], s[60:61]
	s_movk_i32 s16, 0x1600
	v_mad_i64_i32 v[102:103], s[16:17], v78, s16, v[102:103]
	v_lshl_add_u64 v[102:103], v[194:195], 1, v[102:103]
	global_store_dwordx4 v[102:103], v[74:77], off sc1

.LBB0_172:
	s_or_b64 exec, exec, s[40:41]
	v_or_b32_e32 v132, 1, v100
	s_movk_i32 s40, 0x210
	v_mul_lo_u32 v66, v132, s40
	v_add_u32_e32 v131, 0, v66
	v_add_u32_e32 v70, v131, v80
	ds_read_b128 v[66:69], v70
	ds_read_b128 v[70:73], v70 offset:256
	v_fma_f32 v74, v22, v115, v30
	v_fmac_f32_e32 v74, v18, v128
	v_fma_f32 v75, v23, v107, v31
	s_waitcnt lgkmcnt(1)
	v_lshlrev_b32_e32 v119, 16, v66
	v_fma_f32 v74, v26, v119, v74
	v_fmac_f32_e32 v75, v19, v127
	v_mul_f32_e32 v127, 0xbfb8aa3b, v74
	v_exp_f32_e32 v127, v127
	v_fma_f32 v76, v34, v106, v42
	v_and_b32_e32 v118, 0xffff0000, v66
	s_waitcnt lgkmcnt(0)
	v_lshlrev_b32_e32 v117, 16, v70
	v_add_f32_e32 v127, 1.0, v127
	v_rcp_f32_e32 v127, v127
	v_fmac_f32_e32 v76, v62, v130
	v_fma_f32 v75, v27, v118, v75
	v_fma_f32 v76, v38, v117, v76
	v_mul_f32_e32 v74, v74, v127
	v_mul_f32_e32 v74, v76, v74
	v_mul_f32_e32 v76, 0xbfb8aa3b, v75
	v_exp_f32_e32 v76, v76
	v_fma_f32 v77, v35, v99, v43
	v_and_b32_e32 v116, 0xffff0000, v70
	v_fmac_f32_e32 v77, v63, v129
	v_add_f32_e32 v76, 1.0, v76
	v_rcp_f32_e32 v76, v76
	v_fma_f32 v77, v39, v116, v77
	v_lshlrev_b32_e32 v114, 16, v67
	v_mul_f32_e32 v75, v75, v76
	v_mul_f32_e32 v75, v77, v75
	v_cvt_pk_bf16_f32 v74, v74, v75
	v_fma_f32 v75, v24, v98, v32
	v_fmac_f32_e32 v75, v20, v124
	v_fma_f32 v75, v28, v114, v75
	v_mul_f32_e32 v124, 0xbfb8aa3b, v75
	v_exp_f32_e32 v124, v124
	v_fma_f32 v76, v25, v97, v33
	v_fma_f32 v77, v36, v96, v44
	v_and_b32_e32 v113, 0xffff0000, v67
	v_add_f32_e32 v124, 1.0, v124
	v_rcp_f32_e32 v124, v124
	v_lshlrev_b32_e32 v112, 16, v71
	v_fmac_f32_e32 v76, v21, v123
	v_fmac_f32_e32 v77, v64, v126
	v_fma_f32 v76, v29, v113, v76
	v_fma_f32 v77, v40, v112, v77
	v_mul_f32_e32 v75, v75, v124
	v_mul_f32_e32 v75, v77, v75
	v_mul_f32_e32 v77, 0xbfb8aa3b, v76
	v_exp_f32_e32 v77, v77
	v_fma_f32 v123, v37, v95, v45
	v_and_b32_e32 v111, 0xffff0000, v71
	v_fmac_f32_e32 v123, v65, v125
	v_add_f32_e32 v77, 1.0, v77
	v_rcp_f32_e32 v77, v77
	v_fma_f32 v123, v41, v111, v123
	v_lshlrev_b32_e32 v110, 16, v68
	v_mul_f32_e32 v76, v76, v77
	v_mul_f32_e32 v76, v123, v76
	v_cvt_pk_bf16_f32 v75, v75, v76
	v_fma_f32 v76, v6, v94, v14
	v_fmac_f32_e32 v76, v2, v85
	v_fma_f32 v76, v10, v110, v76
	v_fma_f32 v85, v47, v91, v55
	v_fmac_f32_e32 v85, v59, v120
	v_mul_f32_e32 v120, 0xbfb8aa3b, v76
	v_exp_f32_e32 v120, v120
	v_fma_f32 v77, v7, v93, v15
	v_fmac_f32_e32 v77, v3, v84
	v_fma_f32 v84, v46, v92, v54
	v_add_f32_e32 v120, 1.0, v120
	v_rcp_f32_e32 v120, v120
	v_and_b32_e32 v109, 0xffff0000, v68
	v_lshlrev_b32_e32 v108, 16, v72
	v_fmac_f32_e32 v84, v58, v121
	v_fma_f32 v77, v11, v109, v77
	v_fma_f32 v84, v50, v108, v84
	v_mul_f32_e32 v76, v76, v120
	v_mul_f32_e32 v76, v84, v76
	v_mul_f32_e32 v84, 0xbfb8aa3b, v77
	v_exp_f32_e32 v84, v84
	v_and_b32_e32 v105, 0xffff0000, v72
	v_fma_f32 v85, v51, v105, v85
	v_add_f32_e32 v84, 1.0, v84
	v_rcp_f32_e32 v84, v84
	v_and_b32_e32 v103, 0xffff0000, v69
	v_lshlrev_b32_e32 v104, 16, v69
	v_and_b32_e32 v101, 0xffff0000, v73
	v_mul_f32_e32 v77, v77, v84
	v_mul_f32_e32 v77, v85, v77
	v_cvt_pk_bf16_f32 v76, v76, v77
	v_fma_f32 v77, v8, v90, v16
	v_fmac_f32_e32 v77, v4, v81
	v_fma_f32 v81, v9, v89, v17
	v_fmac_f32_e32 v81, v5, v79
	v_fma_f32 v79, v13, v103, v81
	v_fma_f32 v81, v48, v88, v56
	v_fmac_f32_e32 v81, v60, v83
	v_fma_f32 v83, v49, v87, v57
	v_fmac_f32_e32 v83, v61, v82
	v_fma_f32 v77, v12, v104, v77
	v_fma_f32 v82, v53, v101, v83
	v_mul_f32_e32 v83, 0xbfb8aa3b, v77
	v_exp_f32_e32 v83, v83
	v_lshlrev_b32_e32 v102, 16, v73
	v_fma_f32 v81, v52, v102, v81
	v_add_f32_e32 v83, 1.0, v83
	v_rcp_f32_e32 v83, v83
	s_nop 0
	v_mul_f32_e32 v77, v77, v83
	v_mul_f32_e32 v77, v81, v77
	v_mul_f32_e32 v81, 0xbfb8aa3b, v79
	v_exp_f32_e32 v81, v81
	s_nop 0
	v_add_f32_e32 v81, 1.0, v81
	v_rcp_f32_e32 v81, v81
	s_nop 0
	v_mul_f32_e32 v79, v79, v81
	v_mul_f32_e32 v79, v82, v79
	v_cvt_pk_bf16_f32 v77, v77, v79
	s_and_saveexec_b64 s[40:41], vcc
	s_cbranch_execz .LBB0_174
	v_add_u32_e32 v79, s37, v132
	v_mov_b64_e32 v[82:83], s[60:61]
	s_movk_i32 s45, 0x1600
	v_mad_i64_i32 v[82:83], s[68:69], v79, s45, v[82:83]
	v_lshl_add_u64 v[82:83], v[194:195], 1, v[82:83]
	global_store_dwordx4 v[82:83], v[74:77], off sc1

.LBB0_176:
	s_or_b64 exec, exec, s[40:41]
	v_add_u32_e32 v66, 0x210, v131
	v_add_u32_e32 v120, v66, v80
	ds_read_b128 v[66:69], v120
	ds_read_b128 v[124:127], v120 offset:256
	v_cmp_lt_i32_e32 vcc, -1, v86
	s_waitcnt lgkmcnt(1)
	v_lshlrev_b32_e32 v73, 16, v66
	v_and_b32_e32 v71, 0xffff0000, v66
	v_fma_f32 v66, v22, v119, v30
	v_fmac_f32_e32 v66, v18, v115
	v_lshlrev_b32_e32 v85, 16, v69
	v_and_b32_e32 v83, 0xffff0000, v69
	v_fma_f32 v66, v26, v73, v66
	v_fma_f32 v69, v35, v116, v43
	v_fmac_f32_e32 v69, v63, v99
	v_mul_f32_e32 v99, 0xbfb8aa3b, v66
	v_exp_f32_e32 v99, v99
	v_lshlrev_b32_e32 v77, 16, v67
	v_and_b32_e32 v75, 0xffff0000, v67
	v_lshlrev_b32_e32 v81, 16, v68
	v_add_f32_e32 v99, 1.0, v99
	v_rcp_f32_e32 v99, v99
	v_and_b32_e32 v79, 0xffff0000, v68
	v_fma_f32 v67, v23, v118, v31
	v_fma_f32 v68, v34, v117, v42
	s_waitcnt lgkmcnt(0)
	v_lshlrev_b32_e32 v72, 16, v124
	v_fmac_f32_e32 v67, v19, v107
	v_fmac_f32_e32 v68, v62, v106
	v_fma_f32 v67, v27, v71, v67
	v_fma_f32 v68, v38, v72, v68
	v_mul_f32_e32 v66, v66, v99
	v_mul_f32_e32 v66, v68, v66
	v_mul_f32_e32 v68, 0xbfb8aa3b, v67
	v_exp_f32_e32 v68, v68
	v_and_b32_e32 v70, 0xffff0000, v124
	v_fma_f32 v69, v39, v70, v69
	v_add_f32_e32 v68, 1.0, v68
	v_rcp_f32_e32 v68, v68
	v_and_b32_e32 v74, 0xffff0000, v125
	v_lshlrev_b32_e32 v76, 16, v125
	v_lshlrev_b32_e32 v80, 16, v126
	v_mul_f32_e32 v67, v67, v68
	v_mul_f32_e32 v67, v69, v67
	v_cvt_pk_bf16_f32 v66, v66, v67
	v_fma_f32 v67, v24, v114, v32
	v_fma_f32 v69, v36, v112, v44
	v_fmac_f32_e32 v67, v20, v98
	v_fmac_f32_e32 v69, v64, v96
	v_fma_f32 v96, v37, v111, v45
	v_fmac_f32_e32 v96, v65, v95
	v_fma_f32 v67, v28, v77, v67
	v_fma_f32 v95, v41, v74, v96
	v_mul_f32_e32 v96, 0xbfb8aa3b, v67
	v_exp_f32_e32 v96, v96
	v_fma_f32 v68, v25, v113, v33
	v_fmac_f32_e32 v68, v21, v97
	v_add_f32_e32 v96, 1.0, v96
	v_rcp_f32_e32 v96, v96
	v_fma_f32 v68, v29, v75, v68
	v_fma_f32 v69, v40, v76, v69
	v_mul_f32_e32 v67, v67, v96
	v_mul_f32_e32 v67, v69, v67
	v_mul_f32_e32 v69, 0xbfb8aa3b, v68
	v_exp_f32_e32 v69, v69
	v_and_b32_e32 v78, 0xffff0000, v126
	v_lshlrev_b32_e32 v84, 16, v127
	v_and_b32_e32 v82, 0xffff0000, v127
	v_add_f32_e32 v69, 1.0, v69
	v_rcp_f32_e32 v69, v69
	s_nop 0
	v_mul_f32_e32 v68, v68, v69
	v_fma_f32 v69, v7, v109, v15
	v_fmac_f32_e32 v69, v3, v93
	v_fma_f32 v93, v46, v108, v54
	v_mul_f32_e32 v68, v95, v68
	v_fmac_f32_e32 v93, v58, v92
	v_cvt_pk_bf16_f32 v67, v67, v68
	v_fma_f32 v68, v6, v110, v14
	v_fmac_f32_e32 v68, v2, v94
	v_fma_f32 v92, v50, v80, v93
	v_fma_f32 v93, v47, v105, v55
	v_fmac_f32_e32 v93, v59, v91
	v_fma_f32 v68, v10, v81, v68
	v_fma_f32 v91, v51, v78, v93
	v_mul_f32_e32 v93, 0xbfb8aa3b, v68
	v_exp_f32_e32 v93, v93
	v_fma_f32 v69, v11, v79, v69
	v_add_f32_e32 v93, 1.0, v93
	v_rcp_f32_e32 v93, v93
	s_nop 0
	v_mul_f32_e32 v68, v68, v93
	v_mul_f32_e32 v68, v92, v68
	v_mul_f32_e32 v92, 0xbfb8aa3b, v69
	v_exp_f32_e32 v92, v92
	s_nop 0
	v_add_f32_e32 v92, 1.0, v92
	v_rcp_f32_e32 v92, v92
	s_nop 0
	v_mul_f32_e32 v69, v69, v92
	v_mul_f32_e32 v69, v91, v69
	v_cvt_pk_bf16_f32 v68, v68, v69
	v_fma_f32 v69, v8, v104, v16
	v_fmac_f32_e32 v69, v4, v90
	v_fma_f32 v90, v9, v103, v17
	v_fmac_f32_e32 v90, v5, v89
	v_fma_f32 v89, v13, v83, v90
	v_fma_f32 v90, v48, v102, v56
	v_fmac_f32_e32 v90, v60, v88
	v_fma_f32 v88, v52, v84, v90
	v_fma_f32 v90, v49, v101, v57
	v_fmac_f32_e32 v90, v61, v87
	v_fma_f32 v69, v12, v85, v69
	v_fma_f32 v87, v53, v82, v90
	v_mul_f32_e32 v90, 0xbfb8aa3b, v69
	v_exp_f32_e32 v90, v90
	s_nop 0
	v_add_f32_e32 v90, 1.0, v90
	v_rcp_f32_e32 v90, v90
	s_nop 0
	v_mul_f32_e32 v69, v69, v90
	v_mul_f32_e32 v69, v88, v69
	v_mul_f32_e32 v88, 0xbfb8aa3b, v89
	v_exp_f32_e32 v88, v88
	s_nop 0
	v_add_f32_e32 v88, 1.0, v88
	v_rcp_f32_e32 v88, v88
	s_nop 0
	v_mul_f32_e32 v88, v89, v88
	v_mul_f32_e32 v87, v87, v88
	v_cvt_pk_bf16_f32 v69, v69, v87
	s_and_saveexec_b64 s[0:1], vcc
	s_cbranch_execz .LBB0_178
	v_add3_u32 v88, s37, v100, 2
	v_mov_b64_e32 v[86:87], s[60:61]
	s_movk_i32 s40, 0x1600
	v_mad_i64_i32 v[86:87], s[40:41], v88, s40, v[86:87]
	v_lshl_add_u64 v[86:87], v[194:195], 1, v[86:87]
	global_store_dwordx4 v[86:87], v[66:69], off sc1
.LBB0_178:
	s_or_b64 exec, exec, s[0:1]
	ds_read_b128 v[66:69], v120 offset:528
	ds_read_b128 v[124:127], v120 offset:784
	s_waitcnt lgkmcnt(1)
	v_lshlrev_b32_e32 v89, 16, v66
	v_and_b32_e32 v87, 0xffff0000, v66
	v_fma_f32 v66, v22, v73, v30
	v_fmac_f32_e32 v66, v18, v119
	v_fma_f32 v66, v26, v89, v66
	v_mul_f32_e32 v115, 0xbfb8aa3b, v66
	v_exp_f32_e32 v115, v115
	v_lshlrev_b32_e32 v93, 16, v67
	v_and_b32_e32 v91, 0xffff0000, v67
	v_lshlrev_b32_e32 v97, 16, v68
	v_add_f32_e32 v115, 1.0, v115
	v_rcp_f32_e32 v115, v115
	v_and_b32_e32 v95, 0xffff0000, v68
	v_fma_f32 v67, v23, v71, v31
	v_fma_f32 v68, v34, v72, v42
	s_waitcnt lgkmcnt(0)
	v_lshlrev_b32_e32 v88, 16, v124
	v_fmac_f32_e32 v67, v19, v118
	v_fmac_f32_e32 v68, v62, v117
	v_fma_f32 v67, v27, v87, v67
	v_fma_f32 v68, v38, v88, v68
	v_mul_f32_e32 v66, v66, v115
	v_mul_f32_e32 v66, v68, v66
	v_mul_f32_e32 v68, 0xbfb8aa3b, v67
	v_exp_f32_e32 v68, v68
	v_lshlrev_b32_e32 v107, 16, v69
	v_and_b32_e32 v99, 0xffff0000, v69
	v_fma_f32 v69, v35, v70, v43
	v_add_f32_e32 v68, 1.0, v68
	v_rcp_f32_e32 v68, v68
	v_and_b32_e32 v86, 0xffff0000, v124
	v_fmac_f32_e32 v69, v63, v116
	v_fma_f32 v69, v39, v86, v69
	v_mul_f32_e32 v67, v67, v68
	v_mul_f32_e32 v67, v69, v67
	v_cvt_pk_bf16_f32 v66, v66, v67
	v_fma_f32 v67, v24, v77, v32
	v_fma_f32 v69, v36, v76, v44
	v_fmac_f32_e32 v67, v20, v114
	v_fmac_f32_e32 v69, v64, v112
	v_fma_f32 v112, v37, v74, v45
	v_and_b32_e32 v90, 0xffff0000, v125
	v_fmac_f32_e32 v112, v65, v111
	v_fma_f32 v67, v28, v93, v67
	v_fma_f32 v111, v41, v90, v112
	v_mul_f32_e32 v112, 0xbfb8aa3b, v67
	v_exp_f32_e32 v112, v112
	v_fma_f32 v68, v25, v75, v33
	v_lshlrev_b32_e32 v92, 16, v125
	v_fmac_f32_e32 v68, v21, v113
	v_add_f32_e32 v112, 1.0, v112
	v_rcp_f32_e32 v112, v112
	v_fma_f32 v68, v29, v91, v68
	v_fma_f32 v69, v40, v92, v69
	v_mul_f32_e32 v67, v67, v112
	v_mul_f32_e32 v67, v69, v67
	v_mul_f32_e32 v69, 0xbfb8aa3b, v68
	v_exp_f32_e32 v69, v69
	v_lshlrev_b32_e32 v96, 16, v126
	v_and_b32_e32 v94, 0xffff0000, v126
	v_lshlrev_b32_e32 v106, 16, v127
	v_add_f32_e32 v69, 1.0, v69
	v_rcp_f32_e32 v69, v69
	v_and_b32_e32 v98, 0xffff0000, v127
	v_mul_f32_e32 v68, v68, v69
	v_fma_f32 v69, v7, v79, v15
	v_fmac_f32_e32 v69, v3, v109
	v_fma_f32 v109, v46, v80, v54
	v_mul_f32_e32 v68, v111, v68
	v_fmac_f32_e32 v109, v58, v108
	v_cvt_pk_bf16_f32 v67, v67, v68
	v_fma_f32 v68, v6, v81, v14
	v_fmac_f32_e32 v68, v2, v110
	v_fma_f32 v108, v50, v96, v109
	v_fma_f32 v109, v47, v78, v55
	v_fmac_f32_e32 v109, v59, v105
	v_fma_f32 v68, v10, v97, v68
	v_fma_f32 v105, v51, v94, v109
	v_mul_f32_e32 v109, 0xbfb8aa3b, v68
	v_exp_f32_e32 v109, v109
	v_fma_f32 v69, v11, v95, v69
	v_add_f32_e32 v109, 1.0, v109
	v_rcp_f32_e32 v109, v109
	s_nop 0
	v_mul_f32_e32 v68, v68, v109
	v_mul_f32_e32 v68, v108, v68
	v_mul_f32_e32 v108, 0xbfb8aa3b, v69
	v_exp_f32_e32 v108, v108
	s_nop 0
	v_add_f32_e32 v108, 1.0, v108
	v_rcp_f32_e32 v108, v108
	s_nop 0
	v_mul_f32_e32 v69, v69, v108
	v_mul_f32_e32 v69, v105, v69
	v_cvt_pk_bf16_f32 v68, v68, v69
	v_fma_f32 v69, v8, v85, v16
	v_fmac_f32_e32 v69, v4, v104
	v_fma_f32 v104, v9, v83, v17
	v_fmac_f32_e32 v104, v5, v103
	v_fma_f32 v103, v13, v99, v104
	v_fma_f32 v104, v48, v84, v56
	v_fmac_f32_e32 v104, v60, v102
	v_fma_f32 v102, v52, v106, v104
	v_fma_f32 v104, v49, v82, v57
	v_fmac_f32_e32 v104, v61, v101
	v_fma_f32 v69, v12, v107, v69
	v_fma_f32 v101, v53, v98, v104
	v_mul_f32_e32 v104, 0xbfb8aa3b, v69
	v_exp_f32_e32 v104, v104
	s_nop 0
	v_add_f32_e32 v104, 1.0, v104
	v_rcp_f32_e32 v104, v104
	s_nop 0
	v_mul_f32_e32 v69, v69, v104
	v_mul_f32_e32 v69, v102, v69
	v_mul_f32_e32 v102, 0xbfb8aa3b, v103
	v_exp_f32_e32 v102, v102
	s_nop 0
	v_add_f32_e32 v102, 1.0, v102
	v_rcp_f32_e32 v102, v102
	s_nop 0
	v_mul_f32_e32 v102, v103, v102
	v_mul_f32_e32 v101, v101, v102
	v_cvt_pk_bf16_f32 v69, v69, v101
	s_and_saveexec_b64 s[0:1], vcc
	s_cbranch_execz .LBB0_180
	v_add3_u32 v102, s37, v100, 3
	v_mov_b64_e32 v[100:101], s[60:61]
	s_movk_i32 s40, 0x1600
	v_mad_i64_i32 v[100:101], s[40:41], v102, s40, v[100:101]
	v_lshl_add_u64 v[100:101], v[194:195], 1, v[100:101]
	global_store_dwordx4 v[100:101], v[66:69], off sc1
.LBB0_180:
	s_or_b64 exec, exec, s[0:1]
	ds_read_b128 v[124:127], v122 offset:2112
	ds_read_b128 v[128:131], v122 offset:2368
	v_mov_b32_e32 v66, v48
	v_mov_b32_e32 v67, v8
	v_mov_b32_e32 v112, v62
	v_mov_b32_e32 v113, v18
	v_mov_b32_e32 v18, v63
	v_mov_b32_e32 v62, v60
	v_mov_b32_e32 v63, v4
	v_mov_b32_e32 v4, v61
	v_pk_mul_f32 v[60:61], v[66:67], v[106:107]
	v_mov_b32_e32 v8, v49
	v_mov_b32_e32 v110, v64
	v_mov_b32_e32 v111, v20
	v_mov_b32_e32 v20, v65
	v_mov_b32_e32 v100, v58
	v_mov_b32_e32 v101, v2
	v_mov_b32_e32 v2, v59
	v_mov_b32_e32 v64, v52
	v_mov_b32_e32 v65, v12
	s_waitcnt lgkmcnt(1)
	v_lshlrev_b32_e32 v59, 16, v127
	s_waitcnt lgkmcnt(0)
	v_lshlrev_b32_e32 v58, 16, v131
	v_pk_fma_f32 v[60:61], v[62:63], v[84:85], v[60:61]
	v_pk_mul_f32 v[48:49], v[8:9], v[98:99]
	v_mov_b32_e32 v68, v56
	v_mov_b32_e32 v69, v16
	v_pk_fma_f32 v[60:61], v[64:65], v[58:59], v[60:61]
	v_and_b32_e32 v133, 0xffff0000, v127
	v_and_b32_e32 v132, 0xffff0000, v131
	v_pk_fma_f32 v[48:49], v[4:5], v[82:83], v[48:49]
	v_mov_b32_e32 v12, v53
	v_pk_add_f32 v[60:61], v[68:69], v[60:61]
	v_pk_fma_f32 v[48:49], v[12:13], v[132:133], v[48:49]
	v_mov_b32_e32 v16, v57
	v_mov_b32_e32 v105, v6
	v_mul_f32_e32 v6, 0xbfb8aa3b, v61
	v_pk_add_f32 v[48:49], v[16:17], v[48:49]
	v_mov_b32_e32 v103, v10
	v_exp_f32_e32 v6, v6
	v_mul_f32_e32 v10, 0xbfb8aa3b, v49
	v_mov_b32_e32 v104, v46
	v_exp_f32_e32 v10, v10
	v_pk_mul_f32 v[56:57], v[104:105], v[96:97]
	v_mov_b32_e32 v102, v50
	v_lshlrev_b32_e32 v53, 16, v126
	v_lshlrev_b32_e32 v52, 16, v130
	v_pk_fma_f32 v[56:57], v[100:101], v[80:81], v[56:57]
	v_mov_b32_e32 v108, v54
	v_mov_b32_e32 v109, v14
	v_add_f32_e32 v6, 1.0, v6
	v_pk_fma_f32 v[56:57], v[102:103], v[52:53], v[56:57]
	v_rcp_f32_e32 v6, v6
	v_add_f32_e32 v10, 1.0, v10
	v_pk_add_f32 v[56:57], v[108:109], v[56:57]
	v_rcp_f32_e32 v10, v10
	v_mul_f32_e32 v14, 0xbfb8aa3b, v57
	v_exp_f32_e32 v14, v14
	v_mul_f32_e32 v6, v61, v6
	v_mul_f32_e32 v80, v60, v6
	v_mul_f32_e32 v6, v49, v10
	v_mul_f32_e32 v81, v48, v6
	v_add_f32_e32 v6, 1.0, v14
	v_mov_b32_e32 v121, v22
	v_rcp_f32_e32 v22, v6
	v_mov_b32_e32 v6, v47
	v_pk_mul_f32 v[46:47], v[6:7], v[94:95]
	v_and_b32_e32 v49, 0xffff0000, v126
	v_and_b32_e32 v48, 0xffff0000, v130
	v_pk_fma_f32 v[46:47], v[2:3], v[78:79], v[46:47]
	v_mov_b32_e32 v10, v51
	v_pk_fma_f32 v[46:47], v[10:11], v[48:49], v[46:47]
	v_mov_b32_e32 v14, v55
	v_pk_add_f32 v[46:47], v[14:15], v[46:47]
	v_mov_b32_e32 v116, v36
	v_mov_b32_e32 v117, v24
	v_mul_f32_e32 v24, 0xbfb8aa3b, v47
	v_exp_f32_e32 v24, v24
	v_pk_mul_f32 v[54:55], v[116:117], v[92:93]
	v_mov_b32_e32 v114, v40
	v_mov_b32_e32 v115, v28
	v_lshlrev_b32_e32 v51, 16, v125
	v_lshlrev_b32_e32 v50, 16, v129
	v_pk_fma_f32 v[54:55], v[110:111], v[76:77], v[54:55]
	v_mov_b32_e32 v118, v44
	v_mov_b32_e32 v119, v32
	v_pk_fma_f32 v[54:55], v[114:115], v[50:51], v[54:55]
	v_mov_b32_e32 v85, v26
	v_pk_add_f32 v[54:55], v[118:119], v[54:55]
	v_add_f32_e32 v24, 1.0, v24
	v_mul_f32_e32 v26, 0xbfb8aa3b, v55
	v_exp_f32_e32 v26, v26
	v_rcp_f32_e32 v24, v24
	v_mul_f32_e32 v22, v57, v22
	v_mul_f32_e32 v76, v56, v22
	v_add_f32_e32 v26, 1.0, v26
	v_mul_f32_e32 v22, v47, v24
	v_mov_b32_e32 v24, v37
	v_mov_b32_e32 v120, v34
	v_rcp_f32_e32 v26, v26
	v_pk_mul_f32 v[36:37], v[24:25], v[90:91]
	v_mul_f32_e32 v77, v46, v22
	v_and_b32_e32 v47, 0xffff0000, v125
	v_and_b32_e32 v46, 0xffff0000, v129
	v_pk_fma_f32 v[36:37], v[20:21], v[74:75], v[36:37]
	v_mov_b32_e32 v28, v41
	v_pk_mul_f32 v[40:41], v[120:121], v[88:89]
	v_mov_b32_e32 v84, v38
	v_pk_fma_f32 v[36:37], v[28:29], v[46:47], v[36:37]
	v_mov_b32_e32 v32, v45
	v_lshlrev_b32_e32 v57, 16, v124
	v_lshlrev_b32_e32 v56, 16, v128
	v_pk_fma_f32 v[40:41], v[112:113], v[72:73], v[40:41]
	v_mov_b32_e32 v82, v42
	v_mov_b32_e32 v83, v30
	v_pk_add_f32 v[36:37], v[32:33], v[36:37]
	v_pk_fma_f32 v[40:41], v[84:85], v[56:57], v[40:41]
	v_mul_f32_e32 v22, v55, v26
	v_mul_f32_e32 v26, 0xbfb8aa3b, v37
	v_pk_add_f32 v[40:41], v[82:83], v[40:41]
	v_exp_f32_e32 v26, v26
	v_mul_f32_e32 v30, 0xbfb8aa3b, v41
	v_exp_f32_e32 v30, v30
	v_mul_f32_e32 v72, v54, v22
	v_add_f32_e32 v22, 1.0, v26
	v_rcp_f32_e32 v38, v22
	v_add_f32_e32 v22, 1.0, v30
	v_rcp_f32_e32 v42, v22
	v_mov_b32_e32 v22, v35
	v_pk_mul_f32 v[34:35], v[22:23], v[86:87]
	v_and_b32_e32 v55, 0xffff0000, v124
	v_and_b32_e32 v54, 0xffff0000, v128
	v_pk_fma_f32 v[34:35], v[18:19], v[70:71], v[34:35]
	v_mov_b32_e32 v26, v39
	v_pk_fma_f32 v[34:35], v[26:27], v[54:55], v[34:35]
	v_mov_b32_e32 v30, v43
	v_pk_add_f32 v[34:35], v[30:31], v[34:35]
	v_mul_f32_e32 v37, v37, v38
	v_mul_f32_e32 v39, 0xbfb8aa3b, v35
	v_exp_f32_e32 v39, v39
	v_mul_f32_e32 v73, v36, v37
	v_mul_f32_e32 v36, v41, v42
	v_mul_f32_e32 v36, v40, v36
	v_add_f32_e32 v37, 1.0, v39
	v_rcp_f32_e32 v37, v37
	ds_read_b128 v[38:41], v122 offset:2640
	ds_read_b128 v[42:45], v122 offset:2896
	s_mov_b64 vcc, -1
	v_mul_f32_e32 v35, v35, v37
	v_mul_f32_e32 v34, v34, v35
	v_cvt_pk_bf16_f32 v34, v36, v34
	v_pk_mul_f32 v[36:37], v[66:67], v[58:59]
	s_waitcnt lgkmcnt(1)
	v_lshlrev_b32_e32 v71, 16, v41
	s_waitcnt lgkmcnt(0)
	v_lshlrev_b32_e32 v70, 16, v45
	v_pk_fma_f32 v[36:37], v[62:63], v[106:107], v[36:37]
	s_nop 0
	v_pk_fma_f32 v[36:37], v[64:65], v[70:71], v[36:37]
	s_nop 0
	v_pk_add_f32 v[60:61], v[68:69], v[36:37]
	v_cvt_pk_bf16_f32 v36, v76, v77
	v_cvt_pk_bf16_f32 v37, v80, v81
	v_and_b32_e32 v81, 0xffff0000, v39
	v_mul_f32_e32 v35, 0xbfb8aa3b, v61
	v_exp_f32_e32 v74, v35
	v_cvt_pk_bf16_f32 v35, v72, v73
	v_and_b32_e32 v73, 0xffff0000, v41
	v_and_b32_e32 v80, 0xffff0000, v43
	v_add_f32_e32 v72, 1.0, v74
	v_pk_mul_f32 v[74:75], v[8:9], v[132:133]
	v_rcp_f32_e32 v78, v72
	v_and_b32_e32 v72, 0xffff0000, v45
	v_pk_fma_f32 v[74:75], v[4:5], v[98:99], v[74:75]
	v_mul_f32_e32 v45, v61, v78
	v_pk_fma_f32 v[74:75], v[12:13], v[72:73], v[74:75]
	v_pk_fma_f32 v[78:79], v[104:105], v[52:53], v[108:109]
	v_pk_add_f32 v[76:77], v[16:17], v[74:75]
	v_lshlrev_b32_e32 v75, 16, v40
	v_mul_f32_e32 v41, 0xbfb8aa3b, v77
	v_exp_f32_e32 v41, v41
	v_lshlrev_b32_e32 v74, 16, v44
	v_pk_fma_f32 v[78:79], v[100:101], v[96:97], v[78:79]
	v_mul_f32_e32 v98, v60, v45
	v_pk_fma_f32 v[78:79], v[102:103], v[74:75], v[78:79]
	v_add_f32_e32 v41, 1.0, v41
	v_rcp_f32_e32 v41, v41
	v_mul_f32_e32 v45, 0xbfb8aa3b, v79
	v_exp_f32_e32 v45, v45
	v_pk_mul_f32 v[60:61], v[66:67], v[70:71]
	v_mul_f32_e32 v41, v77, v41
	v_mul_f32_e32 v96, v76, v41
	v_add_f32_e32 v41, 1.0, v45
	v_pk_fma_f32 v[60:61], v[62:63], v[58:59], v[60:61]
	v_rcp_f32_e32 v58, v41
	v_and_b32_e32 v77, 0xffff0000, v40
	v_pk_fma_f32 v[40:41], v[6:7], v[48:49], v[14:15]
	v_and_b32_e32 v76, 0xffff0000, v44
	v_pk_fma_f32 v[40:41], v[2:3], v[94:95], v[40:41]
	s_nop 0
	v_pk_fma_f32 v[40:41], v[10:11], v[76:77], v[40:41]
	s_nop 0
	s_nop 0
	v_mul_f32_e32 v44, 0xbfb8aa3b, v41
	v_exp_f32_e32 v59, v44
	v_pk_mul_f32 v[44:45], v[8:9], v[72:73]
	s_nop 0
	v_pk_fma_f32 v[94:95], v[4:5], v[132:133], v[44:45]
	v_mul_f32_e32 v44, v79, v58
	v_add_f32_e32 v45, 1.0, v59
	v_rcp_f32_e32 v58, v45
	v_mul_f32_e32 v97, v78, v44
	v_pk_mul_f32 v[44:45], v[104:105], v[74:75]
	v_lshlrev_b32_e32 v79, 16, v39
	v_pk_fma_f32 v[52:53], v[100:101], v[52:53], v[44:45]
	v_pk_fma_f32 v[44:45], v[116:117], v[50:51], v[118:119]
	v_lshlrev_b32_e32 v78, 16, v43
	v_pk_fma_f32 v[44:45], v[110:111], v[92:93], v[44:45]
	v_mul_f32_e32 v41, v41, v58
	v_pk_fma_f32 v[44:45], v[114:115], v[78:79], v[44:45]
	v_mul_f32_e32 v99, v40, v41
	v_pk_mul_f32 v[40:41], v[6:7], v[76:77]
	v_mul_f32_e32 v58, 0xbfb8aa3b, v45
	v_exp_f32_e32 v58, v58
	v_pk_fma_f32 v[92:93], v[2:3], v[48:49], v[40:41]
	v_add_f32_e32 v40, 1.0, v58
	v_rcp_f32_e32 v48, v40
	v_pk_fma_f32 v[40:41], v[24:25], v[46:47], v[32:33]
	v_mul_f32_e32 v43, v45, v48
	v_pk_fma_f32 v[40:41], v[20:21], v[90:91], v[40:41]
	v_pk_fma_f32 v[48:49], v[120:121], v[56:57], v[82:83]
	v_pk_fma_f32 v[40:41], v[28:29], v[80:81], v[40:41]
	v_lshlrev_b32_e32 v91, 16, v38
	v_lshlrev_b32_e32 v90, 16, v42
	v_mul_f32_e32 v39, 0xbfb8aa3b, v41
	v_exp_f32_e32 v39, v39
	v_pk_fma_f32 v[48:49], v[112:113], v[88:89], v[48:49]
	v_mul_f32_e32 v106, v44, v43
	v_pk_fma_f32 v[48:49], v[84:85], v[90:91], v[48:49]
	v_add_f32_e32 v39, 1.0, v39
	v_rcp_f32_e32 v39, v39
	v_mul_f32_e32 v43, 0xbfb8aa3b, v49
	v_exp_f32_e32 v43, v43
	v_and_b32_e32 v89, 0xffff0000, v38
	v_mul_f32_e32 v39, v41, v39
	v_mul_f32_e32 v107, v40, v39
	v_add_f32_e32 v39, 1.0, v43
	v_rcp_f32_e32 v43, v39
	v_pk_fma_f32 v[38:39], v[22:23], v[54:55], v[30:31]
	v_and_b32_e32 v88, 0xffff0000, v42
	v_pk_fma_f32 v[38:39], v[18:19], v[86:87], v[38:39]
	v_pk_fma_f32 v[44:45], v[116:117], v[78:79], v[118:119]
	v_pk_fma_f32 v[38:39], v[26:27], v[88:89], v[38:39]
	v_pk_fma_f32 v[50:51], v[110:111], v[50:51], v[44:45]
	s_nop 0
	v_mul_f32_e32 v40, 0xbfb8aa3b, v39
	v_exp_f32_e32 v42, v40
	v_pk_fma_f32 v[40:41], v[24:25], v[80:81], v[32:33]
	s_nop 0
	v_pk_fma_f32 v[58:59], v[20:21], v[46:47], v[40:41]
	v_add_f32_e32 v41, 1.0, v42
	v_rcp_f32_e32 v42, v41
	v_mul_f32_e32 v40, v49, v43
	v_mul_f32_e32 v43, v48, v40
	v_pk_fma_f32 v[40:41], v[120:121], v[90:91], v[82:83]
	v_mul_f32_e32 v39, v39, v42
	v_pk_fma_f32 v[56:57], v[112:113], v[56:57], v[40:41]
	v_mul_f32_e32 v40, v38, v39
	v_pk_fma_f32 v[38:39], v[22:23], v[88:89], v[30:31]
	v_cvt_pk_bf16_f32 v46, v43, v40
	v_cvt_pk_bf16_f32 v48, v97, v99
	v_cvt_pk_bf16_f32 v49, v98, v96
	v_cvt_pk_bf16_f32 v47, v106, v107
	s_nop 0
	v_pk_fma_f32 v[54:55], v[18:19], v[54:55], v[38:39]
	ds_read_b128 v[42:45], v122 offset:3168
	ds_read_b128 v[38:41], v122 offset:3424
	s_waitcnt lgkmcnt(1)
	v_lshlrev_b32_e32 v87, 16, v42
	s_waitcnt lgkmcnt(0)
	v_lshlrev_b32_e32 v86, 16, v38
	v_pk_fma_f32 v[56:57], v[84:85], v[86:87], v[56:57]
	v_and_b32_e32 v97, 0xffff0000, v42
	v_and_b32_e32 v96, 0xffff0000, v38
	v_mul_f32_e32 v123, 0xbfb8aa3b, v57
	v_exp_f32_e32 v123, v123
	v_pk_fma_f32 v[54:55], v[26:27], v[96:97], v[54:55]
	v_lshlrev_b32_e32 v99, 16, v43
	v_add_f32_e32 v123, 1.0, v123
	v_mul_f32_e32 v130, 0xbfb8aa3b, v55
	v_exp_f32_e32 v130, v130
	v_rcp_f32_e32 v123, v123
	v_lshlrev_b32_e32 v98, 16, v39
	v_pk_fma_f32 v[50:51], v[114:115], v[98:99], v[50:51]
	v_and_b32_e32 v107, 0xffff0000, v43
	v_and_b32_e32 v106, 0xffff0000, v39
	v_add_f32_e32 v130, 1.0, v130
	v_mul_f32_e32 v57, v57, v123
	v_rcp_f32_e32 v132, v130
	v_mul_f32_e32 v123, v56, v57
	v_pk_fma_f32 v[56:57], v[28:29], v[106:107], v[58:59]
	v_mul_f32_e32 v58, 0xbfb8aa3b, v51
	v_exp_f32_e32 v58, v58
	v_mul_f32_e32 v55, v55, v132
	v_mul_f32_e32 v59, 0xbfb8aa3b, v57
	v_exp_f32_e32 v59, v59
	v_mul_f32_e32 v54, v54, v55
	v_add_f32_e32 v55, 1.0, v58
	v_rcp_f32_e32 v55, v55
	v_add_f32_e32 v58, 1.0, v59
	v_lshlrev_b32_e32 v125, 16, v44
	v_lshlrev_b32_e32 v124, 16, v40
	v_rcp_f32_e32 v59, v58
	v_mul_f32_e32 v51, v51, v55
	v_cvt_pk_bf16_f32 v58, v123, v54
	v_mul_f32_e32 v54, v50, v51
	v_pk_fma_f32 v[50:51], v[102:103], v[124:125], v[52:53]
	v_mul_f32_e32 v55, v57, v59
	v_pk_add_f32 v[50:51], v[108:109], v[50:51]
	v_and_b32_e32 v127, 0xffff0000, v44
	v_mul_f32_e32 v52, 0xbfb8aa3b, v51
	v_exp_f32_e32 v57, v52
	v_and_b32_e32 v126, 0xffff0000, v40
	v_pk_fma_f32 v[52:53], v[10:11], v[126:127], v[92:93]
	v_mul_f32_e32 v55, v56, v55
	v_pk_add_f32 v[52:53], v[14:15], v[52:53]
	v_add_f32_e32 v56, 1.0, v57
	v_rcp_f32_e32 v56, v56
	v_mul_f32_e32 v57, 0xbfb8aa3b, v53
	v_exp_f32_e32 v57, v57
	v_lshlrev_b32_e32 v129, 16, v45
	v_mul_f32_e32 v51, v51, v56
	v_lshlrev_b32_e32 v128, 16, v41
	v_mul_f32_e32 v56, v50, v51
	v_add_f32_e32 v50, 1.0, v57
	v_cvt_pk_bf16_f32 v59, v54, v55
	v_rcp_f32_e32 v54, v50
	v_pk_fma_f32 v[50:51], v[64:65], v[128:129], v[60:61]
	v_and_b32_e32 v131, 0xffff0000, v45
	v_pk_add_f32 v[50:51], v[68:69], v[50:51]
	v_and_b32_e32 v130, 0xffff0000, v41
	v_mul_f32_e32 v55, 0xbfb8aa3b, v51
	v_exp_f32_e32 v57, v55
	v_mul_f32_e32 v53, v53, v54
	v_pk_fma_f32 v[54:55], v[12:13], v[130:131], v[94:95]
	v_mul_f32_e32 v52, v52, v53
	v_pk_add_f32 v[92:93], v[16:17], v[54:55]
	v_add_f32_e32 v54, 1.0, v57
	v_mul_f32_e32 v55, 0xbfb8aa3b, v93
	v_rcp_f32_e32 v54, v54
	v_exp_f32_e32 v55, v55
	v_cvt_pk_bf16_f32 v60, v56, v52
	v_pk_mul_f32 v[86:87], v[120:121], v[86:87]
	v_mul_f32_e32 v51, v51, v54
	v_add_f32_e32 v52, 1.0, v55
	v_rcp_f32_e32 v61, v52
	v_mul_f32_e32 v94, v50, v51
	ds_read_b128 v[54:57], v122 offset:3696
	ds_read_b128 v[50:53], v122 offset:3952
	v_pk_fma_f32 v[86:87], v[112:113], v[90:91], v[86:87]
	v_mul_f32_e32 v61, v93, v61
	v_mul_f32_e32 v61, v92, v61
	s_waitcnt lgkmcnt(1)
	v_lshlrev_b32_e32 v93, 16, v54
	s_waitcnt lgkmcnt(0)
	v_lshlrev_b32_e32 v92, 16, v50
	v_pk_fma_f32 v[22:23], v[22:23], v[96:97], v[30:31]
	v_cvt_pk_bf16_f32 v61, v94, v61
	v_and_b32_e32 v95, 0xffff0000, v54
	v_and_b32_e32 v94, 0xffff0000, v50
	v_pk_fma_f32 v[84:85], v[84:85], v[92:93], v[86:87]
	v_pk_fma_f32 v[18:19], v[18:19], v[88:89], v[22:23]
	v_pk_add_f32 v[82:83], v[82:83], v[84:85]
	v_pk_fma_f32 v[18:19], v[26:27], v[94:95], v[18:19]
	v_mul_f32_e32 v22, 0xbfb8aa3b, v83
	v_exp_f32_e32 v22, v22
	v_mul_f32_e32 v23, 0xbfb8aa3b, v19
	v_exp_f32_e32 v26, v23
	v_pk_fma_f32 v[24:25], v[24:25], v[106:107], v[32:33]
	v_add_f32_e32 v22, 1.0, v22
	v_rcp_f32_e32 v27, v22
	v_add_f32_e32 v22, 1.0, v26
	v_rcp_f32_e32 v26, v22
	v_lshlrev_b32_e32 v123, 16, v55
	v_mul_f32_e32 v27, v83, v27
	v_mul_f32_e32 v30, v82, v27
	v_mul_f32_e32 v19, v19, v26
	v_pk_fma_f32 v[26:27], v[116:117], v[98:99], v[118:119]
	v_lshlrev_b32_e32 v122, 16, v51
	v_and_b32_e32 v133, 0xffff0000, v55
	v_and_b32_e32 v132, 0xffff0000, v51
	v_pk_fma_f32 v[26:27], v[110:111], v[78:79], v[26:27]
	v_pk_fma_f32 v[20:21], v[20:21], v[80:81], v[24:25]
	v_pk_fma_f32 v[26:27], v[114:115], v[122:123], v[26:27]
	v_pk_fma_f32 v[20:21], v[28:29], v[132:133], v[20:21]
	v_mul_f32_e32 v24, 0xbfb8aa3b, v27
	v_mul_f32_e32 v25, 0xbfb8aa3b, v21
	v_exp_f32_e32 v24, v24
	v_exp_f32_e32 v25, v25
	v_mul_f32_e32 v18, v18, v19
	v_pk_fma_f32 v[6:7], v[6:7], v[126:127], v[14:15]
	v_add_f32_e32 v19, 1.0, v24
	v_add_f32_e32 v24, 1.0, v25
	v_rcp_f32_e32 v24, v24
	v_and_b32_e32 v137, 0xffff0000, v56
	v_and_b32_e32 v136, 0xffff0000, v52
	v_pk_fma_f32 v[2:3], v[2:3], v[76:77], v[6:7]
	v_mul_f32_e32 v21, v21, v24
	v_pk_fma_f32 v[24:25], v[104:105], v[124:125], v[108:109]
	v_lshlrev_b32_e32 v135, 16, v56
	v_lshlrev_b32_e32 v134, 16, v52
	v_pk_fma_f32 v[24:25], v[100:101], v[74:75], v[24:25]
	v_pk_fma_f32 v[2:3], v[10:11], v[136:137], v[2:3]
	v_pk_fma_f32 v[24:25], v[102:103], v[134:135], v[24:25]
	v_mul_f32_e32 v7, 0xbfb8aa3b, v3
	v_mul_f32_e32 v6, 0xbfb8aa3b, v25
	v_exp_f32_e32 v7, v7
	v_exp_f32_e32 v6, v6
	v_rcp_f32_e32 v19, v19
	v_mul_f32_e32 v10, v20, v21
	v_add_f32_e32 v7, 1.0, v7
	v_add_f32_e32 v6, 1.0, v6
	v_rcp_f32_e32 v7, v7
	v_rcp_f32_e32 v6, v6
	v_mul_f32_e32 v19, v27, v19
	v_mul_f32_e32 v19, v26, v19
	v_mul_f32_e32 v3, v3, v7
	v_mul_f32_e32 v6, v25, v6
	v_mul_f32_e32 v11, v2, v3
	v_pk_fma_f32 v[2:3], v[66:67], v[128:129], v[68:69]
	v_lshlrev_b32_e32 v139, 16, v57
	v_lshlrev_b32_e32 v138, 16, v53
	v_cvt_pk_bf16_f32 v19, v19, v10
	v_mul_f32_e32 v10, v24, v6
	v_pk_fma_f32 v[2:3], v[62:63], v[70:71], v[2:3]
	v_pk_fma_f32 v[6:7], v[8:9], v[130:131], v[16:17]
	v_and_b32_e32 v23, 0xffff0000, v57
	v_and_b32_e32 v22, 0xffff0000, v53
	v_pk_fma_f32 v[2:3], v[64:65], v[138:139], v[2:3]
	v_pk_fma_f32 v[4:5], v[4:5], v[72:73], v[6:7]
	v_pk_fma_f32 v[4:5], v[12:13], v[22:23], v[4:5]
	v_mul_f32_e32 v6, 0xbfb8aa3b, v3
	v_exp_f32_e32 v6, v6
	v_mul_f32_e32 v7, 0xbfb8aa3b, v5
	v_exp_f32_e32 v7, v7
	s_load_dword s0, s[78:79], 0x0
	v_add_f32_e32 v6, 1.0, v6
	v_rcp_f32_e32 v6, v6
	v_add_f32_e32 v7, 1.0, v7
	v_rcp_f32_e32 v7, v7
	s_waitcnt lgkmcnt(0)
	s_add_i32 s2, s0, s2
	v_mul_f32_e32 v3, v3, v6
	v_mul_f32_e32 v2, v2, v3
	v_mul_f32_e32 v3, v5, v7
	s_cmpk_lt_i32 s2, 0x580
	v_cvt_pk_bf16_f32 v18, v30, v18
	v_cvt_pk_bf16_f32 v20, v10, v11
	v_mul_f32_e32 v3, v4, v3
	v_cvt_pk_bf16_f32 v21, v2, v3
	s_cbranch_scc0 .LBB0_182
	s_mov_b32 s74, s42
	s_mov_b32 s76, s36
	s_branch .LBB0_150
